# K-loops: removed the back-to-back s_setprio 0/1 pair in the middle of each 32-MFMA segment
# speedup vs baseline: 1.0004x; 1.0004x over previous
; #define PG8_STAGE(bufoff, gbase, voff) do { _Pragma("unroll") for (int _i = 0; _i < 2; ++_i) \
;         __builtin_amdgcn_global_load_lds((const unsigned*)((const char*)(gbase) + (voff)[_i]), (LAS unsigned*)(lds + (bufoff) + ldsw + _i * 8192), 16, 0, 0); } while (0)
; #define PG8_LDA(dst, b, h) do { _Pragma("unroll") for (int m = 0; m < 4; ++m) _Pragma("unroll") for (int k = 0; k < 2; ++k) dst[m][k] = *(const LAS bf16x8*)(lds + PG8_SA(b, h) + aoff + m * 2048 + k * 1024); } while (0)
; #define PG8_LDB(dst, b, h) do { _Pragma("unroll") for (int n = 0; n < 2; ++n) _Pragma("unroll") for (int k = 0; k < 2; ++k) dst[n][k] = *(const LAS bf16x8*)(lds + PG8_SB(b, h) + boff + n * 2048 + k * 1024); } while (0)
; #define PG8_MMA(ai, bj, At, Bt) do { __builtin_amdgcn_s_setprio(1); _Pragma("unroll") for (int m = 0; m < 4; ++m) _Pragma("unroll") for (int n = 0; n < 2; ++n) _Pragma("unroll") for (int k = 0; k < 2; ++k) \
;         acc[ai][bj][m][n] = __builtin_amdgcn_mfma_f32_16x16x32_bf16(Bt[n][k], At[m][k], acc[ai][bj][m][n], 0, 0, 0); __builtin_amdgcn_s_setprio(0); } while (0)
; #define PG8_WAIT_V(n) asm volatile("s_waitcnt vmcnt(" #n ")" ::: "memory")
; #define PG8_WAIT_L(n) asm volatile("s_waitcnt lgkmcnt(" #n ")" ::: "memory")
; #define PG8_BAR __builtin_amdgcn_s_barrier()
; #define PG8_SCHED __builtin_amdgcn_sched_barrier(0)
;     ...
;         for (int t = 0; t < nt; t += 2) {
;             const bool last = (t == nt - 2);
;             const char* a1 = cA + (size_t)(t + 1) * kstep;
;             const char* a2 = last ? nA : cA + (size_t)(t + 2) * kstep; const char* b2 = last ? nB : cB + (size_t)(t + 2) * kstep;
;             const char* a3 = a2 + kstep; const char* b3 = b2 + kstep;
;             PG8_LDB(B0, 0, 0); PG8_LDB(B1, 0, 1); PG8_SCHED; PG8_LDA(At, 0, 0); PG8_STAGE(PG8_SA(1, 1), a1 + hstepA, voffA);
;             PG8_WAIT_V(8); PG8_WAIT_L(0); PG8_BAR; PG8_MMA(0, 0, At, B0); PG8_MMA(0, 1, At, B1); PG8_BAR; PG8_SCHED;
;             PG8_LDA(At, 0, 1); PG8_STAGE(PG8_SB(0, 0), b2, voffB); PG8_STAGE(PG8_SB(0, 1), b2 + hstepB, voffB); PG8_STAGE(PG8_SA(0, 0), a2, voffA);
;             PG8_WAIT_V(8); PG8_WAIT_L(0); PG8_BAR; PG8_MMA(1, 0, At, B0); PG8_MMA(1, 1, At, B1); PG8_BAR; PG8_SCHED;
.LBB0_159:
	s_add_i32 s38, s8, 2
	s_add_u32 s26, s12, s0
	s_addc_u32 s9, s13, s1
	s_add_i32 s27, 0, 0x10000
	s_cmp_eq_u32 s63, s8
	s_cselect_b32 s9, s18, s9
	s_cselect_b32 s8, s19, s26
	s_cselect_b64 vcc, -1, 0
	s_add_i32 s26, 0, 0x14000
	v_lshl_add_u64 v[150:151], v[188:189], 0, s[0:1]
	v_add_u32_e32 v146, s27, v226
	v_add_u32_e32 v162, s26, v226
	ds_read_b128 v[134:137], v146
	ds_read_b128 v[138:141], v146 offset:1024
	ds_read_b128 v[142:145], v146 offset:2048
	ds_read_b128 v[146:149], v146 offset:3072
	v_cndmask_b32_e32 v205, v151, v132, vcc
	v_cndmask_b32_e32 v204, v150, v133, vcc
	ds_read_b128 v[150:153], v162
	ds_read_b128 v[154:157], v162 offset:1024
	ds_read_b128 v[158:161], v162 offset:2048
	ds_read_b128 v[162:165], v162 offset:3072
	v_lshl_add_u64 v[212:213], s[12:13], 0, v[130:131]
	s_add_i32 m0, s20, 0xc000
	ds_read_b128 v[166:169], v227
	ds_read_b128 v[170:173], v227 offset:1024
	ds_read_b128 v[174:177], v227 offset:2048
	ds_read_b128 v[178:181], v227 offset:3072
	ds_read_b128 v[230:233], v227 offset:4096
	ds_read_b128 v[234:237], v227 offset:5120
	ds_read_b128 v[238:241], v227 offset:6144
	ds_read_b128 v[242:245], v227 offset:7168
	global_load_lds_dwordx4 v[212:213], off
	v_lshl_add_u64 v[212:213], s[12:13], 0, v[128:129]
	s_add_i32 m0, s20, 0xe000
	s_nop 0
	global_load_lds_dwordx4 v[212:213], off
	s_waitcnt vmcnt(8)
	s_waitcnt lgkmcnt(0)
	s_barrier
	s_setprio 1
	s_waitcnt lgkmcnt(0)
	v_mfma_f32_16x16x32_bf16 v[124:127], v[134:137], v[166:169], v[124:127]
	v_mfma_f32_16x16x32_bf16 v[0:3], v[142:145], v[166:169], v[0:3]
	v_mfma_f32_16x16x32_bf16 v[120:123], v[134:137], v[174:177], v[120:123]
	v_mfma_f32_16x16x32_bf16 v[116:119], v[142:145], v[174:177], v[116:119]
	v_mfma_f32_16x16x32_bf16 v[112:115], v[134:137], v[230:233], v[112:115]
	v_mfma_f32_16x16x32_bf16 v[108:111], v[142:145], v[230:233], v[108:111]
	v_mfma_f32_16x16x32_bf16 v[104:107], v[134:137], v[238:241], v[104:107]
	v_mfma_f32_16x16x32_bf16 v[4:7], v[142:145], v[238:241], v[4:7]
	v_mfma_f32_16x16x32_bf16 v[124:127], v[138:141], v[170:173], v[124:127]
	v_mfma_f32_16x16x32_bf16 v[0:3], v[146:149], v[170:173], v[0:3]
	v_mfma_f32_16x16x32_bf16 v[120:123], v[138:141], v[178:181], v[120:123]
	v_mfma_f32_16x16x32_bf16 v[116:119], v[146:149], v[178:181], v[116:119]
	v_mfma_f32_16x16x32_bf16 v[112:115], v[138:141], v[234:237], v[112:115]
	v_mfma_f32_16x16x32_bf16 v[108:111], v[146:149], v[234:237], v[108:111]
	v_mfma_f32_16x16x32_bf16 v[104:107], v[138:141], v[242:245], v[104:107]
	v_mfma_f32_16x16x32_bf16 v[4:7], v[146:149], v[242:245], v[4:7]
	v_mfma_f32_16x16x32_bf16 v[100:103], v[150:153], v[166:169], v[100:103]
	v_mfma_f32_16x16x32_bf16 v[96:99], v[158:161], v[166:169], v[96:99]
	v_mfma_f32_16x16x32_bf16 v[92:95], v[150:153], v[174:177], v[92:95]
	v_mfma_f32_16x16x32_bf16 v[88:91], v[158:161], v[174:177], v[88:91]
	v_mfma_f32_16x16x32_bf16 v[84:87], v[150:153], v[230:233], v[84:87]
	v_mfma_f32_16x16x32_bf16 v[80:83], v[158:161], v[230:233], v[80:83]
	v_mfma_f32_16x16x32_bf16 v[76:79], v[150:153], v[238:241], v[76:79]
	v_mfma_f32_16x16x32_bf16 v[72:75], v[158:161], v[238:241], v[72:75]
	v_mfma_f32_16x16x32_bf16 v[100:103], v[154:157], v[170:173], v[100:103]
	v_mfma_f32_16x16x32_bf16 v[96:99], v[162:165], v[170:173], v[96:99]
	v_mfma_f32_16x16x32_bf16 v[92:95], v[154:157], v[178:181], v[92:95]
	v_mfma_f32_16x16x32_bf16 v[88:91], v[162:165], v[178:181], v[88:91]
	v_mfma_f32_16x16x32_bf16 v[84:87], v[154:157], v[234:237], v[84:87]
	v_mfma_f32_16x16x32_bf16 v[80:83], v[162:165], v[234:237], v[80:83]
	v_mfma_f32_16x16x32_bf16 v[76:79], v[154:157], v[242:245], v[76:79]
	v_mfma_f32_16x16x32_bf16 v[72:75], v[162:165], v[242:245], v[72:75]
	s_setprio 0
	s_barrier
	s_add_i32 s27, s27, s11
	v_lshl_add_u64 v[212:213], v[204:205], 0, v[192:193]
	s_mov_b32 m0, s27
	ds_read_b128 v[166:169], v227 offset:16384
	ds_read_b128 v[170:173], v227 offset:17408
	ds_read_b128 v[174:177], v227 offset:18432
	ds_read_b128 v[178:181], v227 offset:19456
	ds_read_b128 v[230:233], v227 offset:20480
	ds_read_b128 v[234:237], v227 offset:21504
	ds_read_b128 v[238:241], v227 offset:22528
	ds_read_b128 v[242:245], v227 offset:23552
	global_load_lds_dwordx4 v[212:213], off
	v_lshl_add_u64 v[218:219], v[204:205], 0, v[196:197]
	s_add_i32 m0, s27, 0x2000
	v_lshl_add_u64 v[204:205], v[204:205], 0, v[198:199]
	s_add_i32 s26, s26, s11
	global_load_lds_dwordx4 v[218:219], off
	v_lshl_add_u64 v[246:247], v[204:205], 0, v[192:193]
	s_mov_b32 m0, s26
	v_lshl_add_u64 v[204:205], v[204:205], 0, v[196:197]
	global_load_lds_dwordx4 v[246:247], off
	s_add_i32 m0, s26, 0x2000
	v_lshl_add_u64 v[248:249], s[8:9], 0, v[190:191]
	global_load_lds_dwordx4 v[204:205], off
	s_mov_b32 m0, s20
	v_lshl_add_u64 v[250:251], s[8:9], 0, v[194:195]
	global_load_lds_dwordx4 v[248:249], off
	s_mov_b32 m0, s48
	s_nop 0
	global_load_lds_dwordx4 v[250:251], off
	s_waitcnt vmcnt(8)
	s_waitcnt lgkmcnt(0)
	s_barrier
; #define PG8_STAGE(bufoff, gbase, voff) do { _Pragma("unroll") for (int _i = 0; _i < 2; ++_i) \
;         __builtin_amdgcn_global_load_lds((const unsigned*)((const char*)(gbase) + (voff)[_i]), (LAS unsigned*)(lds + (bufoff) + ldsw + _i * 8192), 16, 0, 0); } while (0)
; #define PG8_LDA(dst, b, h) do { _Pragma("unroll") for (int m = 0; m < 4; ++m) _Pragma("unroll") for (int k = 0; k < 2; ++k) dst[m][k] = *(const LAS bf16x8*)(lds + PG8_SA(b, h) + aoff + m * 2048 + k * 1024); } while (0)
; #define PG8_LDB(dst, b, h) do { _Pragma("unroll") for (int n = 0; n < 2; ++n) _Pragma("unroll") for (int k = 0; k < 2; ++k) dst[n][k] = *(const LAS bf16x8*)(lds + PG8_SB(b, h) + boff + n * 2048 + k * 1024); } while (0)
; #define PG8_MMA(ai, bj, At, Bt) do { __builtin_amdgcn_s_setprio(1); _Pragma("unroll") for (int m = 0; m < 4; ++m) _Pragma("unroll") for (int n = 0; n < 2; ++n) _Pragma("unroll") for (int k = 0; k < 2; ++k) \
;         acc[ai][bj][m][n] = __builtin_amdgcn_mfma_f32_16x16x32_bf16(Bt[n][k], At[m][k], acc[ai][bj][m][n], 0, 0, 0); __builtin_amdgcn_s_setprio(0); } while (0)
; #define PG8_WAIT_V(n) asm volatile("s_waitcnt vmcnt(" #n ")" ::: "memory")
; #define PG8_WAIT_L(n) asm volatile("s_waitcnt lgkmcnt(" #n ")" ::: "memory")
; #define PG8_BAR __builtin_amdgcn_s_barrier()
; #define PG8_SCHED __builtin_amdgcn_sched_barrier(0)
;     ...
;             PG8_WAIT_V(8); PG8_WAIT_L(0); PG8_BAR; PG8_MMA(1, 0, At, B0); PG8_MMA(1, 1, At, B1); PG8_BAR; PG8_SCHED;
;             PG8_LDB(B0, 1, 0); PG8_LDB(B1, 1, 1); PG8_SCHED; PG8_LDA(At, 1, 0); PG8_STAGE(PG8_SA(0, 1), a2 + hstepA, voffA);
;             PG8_WAIT_V(8); PG8_WAIT_L(0); PG8_BAR; PG8_MMA(0, 0, At, B0); PG8_MMA(0, 1, At, B1); PG8_BAR; PG8_SCHED;
	s_setprio 1
	s_waitcnt lgkmcnt(0)
	v_mfma_f32_16x16x32_bf16 v[68:71], v[134:137], v[166:169], v[68:71]
	v_mfma_f32_16x16x32_bf16 v[8:11], v[142:145], v[166:169], v[8:11]
	v_mfma_f32_16x16x32_bf16 v[64:67], v[134:137], v[174:177], v[64:67]
	v_mfma_f32_16x16x32_bf16 v[60:63], v[142:145], v[174:177], v[60:63]
	v_mfma_f32_16x16x32_bf16 v[56:59], v[134:137], v[230:233], v[56:59]
	v_mfma_f32_16x16x32_bf16 v[52:55], v[142:145], v[230:233], v[52:55]
	v_mfma_f32_16x16x32_bf16 v[48:51], v[134:137], v[238:241], v[48:51]
	v_mfma_f32_16x16x32_bf16 v[12:15], v[142:145], v[238:241], v[12:15]
	v_mfma_f32_16x16x32_bf16 v[68:71], v[138:141], v[170:173], v[68:71]
	v_mfma_f32_16x16x32_bf16 v[8:11], v[146:149], v[170:173], v[8:11]
	v_mfma_f32_16x16x32_bf16 v[64:67], v[138:141], v[178:181], v[64:67]
	v_mfma_f32_16x16x32_bf16 v[60:63], v[146:149], v[178:181], v[60:63]
	v_mfma_f32_16x16x32_bf16 v[56:59], v[138:141], v[234:237], v[56:59]
	v_mfma_f32_16x16x32_bf16 v[52:55], v[146:149], v[234:237], v[52:55]
	v_mfma_f32_16x16x32_bf16 v[48:51], v[138:141], v[242:245], v[48:51]
	v_mfma_f32_16x16x32_bf16 v[12:15], v[146:149], v[242:245], v[12:15]
	v_mfma_f32_16x16x32_bf16 v[44:47], v[150:153], v[166:169], v[44:47]
	v_mfma_f32_16x16x32_bf16 v[40:43], v[158:161], v[166:169], v[40:43]
	v_mfma_f32_16x16x32_bf16 v[36:39], v[150:153], v[174:177], v[36:39]
	v_mfma_f32_16x16x32_bf16 v[32:35], v[158:161], v[174:177], v[32:35]
	v_mfma_f32_16x16x32_bf16 v[28:31], v[150:153], v[230:233], v[28:31]
	v_mfma_f32_16x16x32_bf16 v[24:27], v[158:161], v[230:233], v[24:27]
	v_mfma_f32_16x16x32_bf16 v[20:23], v[150:153], v[238:241], v[20:23]
	v_mfma_f32_16x16x32_bf16 v[16:19], v[158:161], v[238:241], v[16:19]
	v_mfma_f32_16x16x32_bf16 v[44:47], v[154:157], v[170:173], v[44:47]
	v_mfma_f32_16x16x32_bf16 v[40:43], v[162:165], v[170:173], v[40:43]
	v_mfma_f32_16x16x32_bf16 v[36:39], v[154:157], v[178:181], v[36:39]
	v_mfma_f32_16x16x32_bf16 v[32:35], v[162:165], v[178:181], v[32:35]
	v_mfma_f32_16x16x32_bf16 v[28:31], v[154:157], v[234:237], v[28:31]
	v_mfma_f32_16x16x32_bf16 v[24:27], v[162:165], v[234:237], v[24:27]
	v_mfma_f32_16x16x32_bf16 v[20:23], v[154:157], v[242:245], v[20:23]
	v_mfma_f32_16x16x32_bf16 v[16:19], v[162:165], v[242:245], v[16:19]
	s_setprio 0
	s_barrier
	s_add_i32 s26, 0, 0x18000
	s_add_i32 s27, 0, 0x1c000
	v_add_u32_e32 v146, s26, v226
	v_add_u32_e32 v162, s27, v226
	ds_read_b128 v[134:137], v146
	ds_read_b128 v[138:141], v146 offset:1024
	ds_read_b128 v[142:145], v146 offset:2048
	ds_read_b128 v[146:149], v146 offset:3072
	ds_read_b128 v[150:153], v162
	ds_read_b128 v[154:157], v162 offset:1024
	ds_read_b128 v[158:161], v162 offset:2048
	ds_read_b128 v[162:165], v162 offset:3072
	s_add_u32 s8, s8, s10
	s_addc_u32 s9, s9, 0
	s_mov_b32 m0, s51
	v_lshl_add_u64 v[214:215], s[8:9], 0, v[190:191]
	ds_read_b128 v[166:169], v227 offset:32768
	ds_read_b128 v[170:173], v227 offset:33792
	ds_read_b128 v[174:177], v227 offset:34816
	ds_read_b128 v[178:181], v227 offset:35840
	ds_read_b128 v[230:233], v227 offset:36864
	ds_read_b128 v[234:237], v227 offset:37888
	ds_read_b128 v[238:241], v227 offset:38912
	ds_read_b128 v[242:245], v227 offset:39936
	global_load_lds_dwordx4 v[214:215], off
	v_lshl_add_u64 v[214:215], s[8:9], 0, v[194:195]
	s_mov_b32 m0, s62
	s_nop 0
	global_load_lds_dwordx4 v[214:215], off
	s_waitcnt vmcnt(8)
	s_waitcnt lgkmcnt(0)
	s_barrier
	s_setprio 1
	s_waitcnt lgkmcnt(0)
	v_mfma_f32_16x16x32_bf16 v[124:127], v[134:137], v[166:169], v[124:127]
	v_mfma_f32_16x16x32_bf16 v[0:3], v[142:145], v[166:169], v[0:3]
	v_mfma_f32_16x16x32_bf16 v[120:123], v[134:137], v[174:177], v[120:123]
	v_mfma_f32_16x16x32_bf16 v[116:119], v[142:145], v[174:177], v[116:119]
	v_mfma_f32_16x16x32_bf16 v[112:115], v[134:137], v[230:233], v[112:115]
	v_mfma_f32_16x16x32_bf16 v[108:111], v[142:145], v[230:233], v[108:111]
	v_mfma_f32_16x16x32_bf16 v[104:107], v[134:137], v[238:241], v[104:107]
	v_mfma_f32_16x16x32_bf16 v[4:7], v[142:145], v[238:241], v[4:7]
	v_mfma_f32_16x16x32_bf16 v[124:127], v[138:141], v[170:173], v[124:127]
	v_mfma_f32_16x16x32_bf16 v[0:3], v[146:149], v[170:173], v[0:3]
	v_mfma_f32_16x16x32_bf16 v[120:123], v[138:141], v[178:181], v[120:123]
	v_mfma_f32_16x16x32_bf16 v[116:119], v[146:149], v[178:181], v[116:119]
	v_mfma_f32_16x16x32_bf16 v[112:115], v[138:141], v[234:237], v[112:115]
	v_mfma_f32_16x16x32_bf16 v[108:111], v[146:149], v[234:237], v[108:111]
	v_mfma_f32_16x16x32_bf16 v[104:107], v[138:141], v[242:245], v[104:107]
	v_mfma_f32_16x16x32_bf16 v[4:7], v[146:149], v[242:245], v[4:7]
	v_mfma_f32_16x16x32_bf16 v[100:103], v[150:153], v[166:169], v[100:103]
	v_mfma_f32_16x16x32_bf16 v[96:99], v[158:161], v[166:169], v[96:99]
	v_mfma_f32_16x16x32_bf16 v[92:95], v[150:153], v[174:177], v[92:95]
	v_mfma_f32_16x16x32_bf16 v[88:91], v[158:161], v[174:177], v[88:91]
	v_mfma_f32_16x16x32_bf16 v[84:87], v[150:153], v[230:233], v[84:87]
	v_mfma_f32_16x16x32_bf16 v[80:83], v[158:161], v[230:233], v[80:83]
	v_mfma_f32_16x16x32_bf16 v[76:79], v[150:153], v[238:241], v[76:79]
	v_mfma_f32_16x16x32_bf16 v[72:75], v[158:161], v[238:241], v[72:75]
	v_mfma_f32_16x16x32_bf16 v[100:103], v[154:157], v[170:173], v[100:103]
	v_mfma_f32_16x16x32_bf16 v[96:99], v[162:165], v[170:173], v[96:99]
	v_mfma_f32_16x16x32_bf16 v[92:95], v[154:157], v[178:181], v[92:95]
	v_mfma_f32_16x16x32_bf16 v[88:91], v[162:165], v[178:181], v[88:91]
	v_mfma_f32_16x16x32_bf16 v[84:87], v[154:157], v[234:237], v[84:87]
	v_mfma_f32_16x16x32_bf16 v[80:83], v[162:165], v[234:237], v[80:83]
	v_mfma_f32_16x16x32_bf16 v[76:79], v[154:157], v[242:245], v[76:79]
	v_mfma_f32_16x16x32_bf16 v[72:75], v[162:165], v[242:245], v[72:75]
	s_setprio 0
	s_barrier
; #define PG8_STAGE(bufoff, gbase, voff) do { _Pragma("unroll") for (int _i = 0; _i < 2; ++_i) \
;         __builtin_amdgcn_global_load_lds((const unsigned*)((const char*)(gbase) + (voff)[_i]), (LAS unsigned*)(lds + (bufoff) + ldsw + _i * 8192), 16, 0, 0); } while (0)
; #define PG8_LDA(dst, b, h) do { _Pragma("unroll") for (int m = 0; m < 4; ++m) _Pragma("unroll") for (int k = 0; k < 2; ++k) dst[m][k] = *(const LAS bf16x8*)(lds + PG8_SA(b, h) + aoff + m * 2048 + k * 1024); } while (0)
; #define PG8_MMA(ai, bj, At, Bt) do { __builtin_amdgcn_s_setprio(1); _Pragma("unroll") for (int m = 0; m < 4; ++m) _Pragma("unroll") for (int n = 0; n < 2; ++n) _Pragma("unroll") for (int k = 0; k < 2; ++k) \
;         acc[ai][bj][m][n] = __builtin_amdgcn_mfma_f32_16x16x32_bf16(Bt[n][k], At[m][k], acc[ai][bj][m][n], 0, 0, 0); __builtin_amdgcn_s_setprio(0); } while (0)
; #define PG8_WAIT_V(n) asm volatile("s_waitcnt vmcnt(" #n ")" ::: "memory")
; #define PG8_WAIT_L(n) asm volatile("s_waitcnt lgkmcnt(" #n ")" ::: "memory")
; #define PG8_BAR __builtin_amdgcn_s_barrier()
; #define PG8_SCHED __builtin_amdgcn_sched_barrier(0)
;     ...
;             PG8_LDA(At, 1, 1); PG8_STAGE(PG8_SB(1, 0), b3, voffB); PG8_STAGE(PG8_SB(1, 1), b3 + hstepB, voffB); PG8_STAGE(PG8_SA(1, 0), a3, voffA);
;             PG8_WAIT_V(8); PG8_WAIT_L(0); PG8_BAR; PG8_MMA(1, 0, At, B0); PG8_MMA(1, 1, At, B1); PG8_BAR; PG8_SCHED;
;         }
;         if (wr == 0) PG8_BAR;
	s_add_i32 s8, s26, s11
	v_lshl_add_u64 v[212:213], v[212:213], 0, s[70:71]
	s_mov_b32 m0, s8
	ds_read_b128 v[166:169], v227 offset:49152
	ds_read_b128 v[170:173], v227 offset:50176
	ds_read_b128 v[174:177], v227 offset:51200
	ds_read_b128 v[178:181], v227 offset:52224
	ds_read_b128 v[230:233], v227 offset:53248
	ds_read_b128 v[234:237], v227 offset:54272
	ds_read_b128 v[238:241], v227 offset:55296
	ds_read_b128 v[242:245], v227 offset:56320
	global_load_lds_dwordx4 v[212:213], off
	v_lshl_add_u64 v[212:213], v[218:219], 0, s[70:71]
	s_add_i32 m0, s8, 0x2000
	s_add_i32 s8, s27, s11
	global_load_lds_dwordx4 v[212:213], off
	v_lshl_add_u64 v[212:213], v[246:247], 0, s[70:71]
	s_mov_b32 m0, s8
	v_lshl_add_u64 v[204:205], v[204:205], 0, s[70:71]
	global_load_lds_dwordx4 v[212:213], off
	s_add_i32 m0, s8, 0x2000
	s_nop 0
	global_load_lds_dwordx4 v[204:205], off
	v_lshl_add_u64 v[204:205], v[248:249], 0, s[70:71]
	s_mov_b32 m0, s65
	s_nop 0
	global_load_lds_dwordx4 v[204:205], off
	v_lshl_add_u64 v[204:205], v[250:251], 0, s[70:71]
	s_mov_b32 m0, s49
	s_nop 0
	global_load_lds_dwordx4 v[204:205], off
	s_waitcnt vmcnt(8)
	s_waitcnt lgkmcnt(0)
	s_barrier
	s_setprio 1
	s_waitcnt lgkmcnt(0)
	v_mfma_f32_16x16x32_bf16 v[68:71], v[134:137], v[166:169], v[68:71]
	v_mfma_f32_16x16x32_bf16 v[8:11], v[142:145], v[166:169], v[8:11]
	v_mfma_f32_16x16x32_bf16 v[64:67], v[134:137], v[174:177], v[64:67]
	v_mfma_f32_16x16x32_bf16 v[60:63], v[142:145], v[174:177], v[60:63]
	v_mfma_f32_16x16x32_bf16 v[56:59], v[134:137], v[230:233], v[56:59]
	v_mfma_f32_16x16x32_bf16 v[52:55], v[142:145], v[230:233], v[52:55]
	v_mfma_f32_16x16x32_bf16 v[48:51], v[134:137], v[238:241], v[48:51]
	v_mfma_f32_16x16x32_bf16 v[12:15], v[142:145], v[238:241], v[12:15]
	v_mfma_f32_16x16x32_bf16 v[68:71], v[138:141], v[170:173], v[68:71]
	v_mfma_f32_16x16x32_bf16 v[8:11], v[146:149], v[170:173], v[8:11]
	v_mfma_f32_16x16x32_bf16 v[64:67], v[138:141], v[178:181], v[64:67]
	v_mfma_f32_16x16x32_bf16 v[60:63], v[146:149], v[178:181], v[60:63]
	v_mfma_f32_16x16x32_bf16 v[56:59], v[138:141], v[234:237], v[56:59]
	v_mfma_f32_16x16x32_bf16 v[52:55], v[146:149], v[234:237], v[52:55]
	v_mfma_f32_16x16x32_bf16 v[48:51], v[138:141], v[242:245], v[48:51]
	v_mfma_f32_16x16x32_bf16 v[12:15], v[146:149], v[242:245], v[12:15]
	v_mfma_f32_16x16x32_bf16 v[44:47], v[150:153], v[166:169], v[44:47]
	v_mfma_f32_16x16x32_bf16 v[40:43], v[158:161], v[166:169], v[40:43]
	v_mfma_f32_16x16x32_bf16 v[36:39], v[150:153], v[174:177], v[36:39]
	v_mfma_f32_16x16x32_bf16 v[32:35], v[158:161], v[174:177], v[32:35]
	v_mfma_f32_16x16x32_bf16 v[28:31], v[150:153], v[230:233], v[28:31]
	v_mfma_f32_16x16x32_bf16 v[24:27], v[158:161], v[230:233], v[24:27]
	v_mfma_f32_16x16x32_bf16 v[20:23], v[150:153], v[238:241], v[20:23]
	v_mfma_f32_16x16x32_bf16 v[16:19], v[158:161], v[238:241], v[16:19]
	v_mfma_f32_16x16x32_bf16 v[44:47], v[154:157], v[170:173], v[44:47]
	v_mfma_f32_16x16x32_bf16 v[40:43], v[162:165], v[170:173], v[40:43]
	v_mfma_f32_16x16x32_bf16 v[36:39], v[154:157], v[178:181], v[36:39]
	v_mfma_f32_16x16x32_bf16 v[32:35], v[162:165], v[178:181], v[32:35]
	v_mfma_f32_16x16x32_bf16 v[28:31], v[154:157], v[234:237], v[28:31]
	v_mfma_f32_16x16x32_bf16 v[24:27], v[162:165], v[234:237], v[24:27]
	v_mfma_f32_16x16x32_bf16 v[20:23], v[154:157], v[242:245], v[20:23]
	v_mfma_f32_16x16x32_bf16 v[16:19], v[162:165], v[242:245], v[16:19]
	s_setprio 0
	s_barrier
	s_add_u32 s0, s0, 0x100
	s_addc_u32 s1, s1, 0
	v_lshl_add_u64 v[130:131], v[130:131], 0, s[94:95]
	v_lshl_add_u64 v[128:129], v[128:129], 0, s[94:95]
	s_cmp_ge_u32 s38, s52
	s_mov_b32 s8, s38
	s_cbranch_scc0 .LBB0_159
	v_readlane_b32 s0, v254, 50
	v_readlane_b32 s1, v254, 51
	s_and_b64 vcc, exec, s[0:1]
	s_movk_i32 s67, 0xfe
	s_cbranch_vccz .LBB0_162
	s_barrier

; #define PG8_STAGE(bufoff, gbase, voff) do { _Pragma("unroll") for (int _i = 0; _i < 2; ++_i) \
;         __builtin_amdgcn_global_load_lds((const unsigned*)((const char*)(gbase) + (voff)[_i]), (LAS unsigned*)(lds + (bufoff) + ldsw + _i * 8192), 16, 0, 0); } while (0)
; #define PG8_LDA(dst, b, h) do { _Pragma("unroll") for (int m = 0; m < 4; ++m) _Pragma("unroll") for (int k = 0; k < 2; ++k) dst[m][k] = *(const LAS bf16x8*)(lds + PG8_SA(b, h) + aoff + m * 2048 + k * 1024); } while (0)
; #define PG8_LDB(dst, b, h) do { _Pragma("unroll") for (int n = 0; n < 2; ++n) _Pragma("unroll") for (int k = 0; k < 2; ++k) dst[n][k] = *(const LAS bf16x8*)(lds + PG8_SB(b, h) + boff + n * 2048 + k * 1024); } while (0)
; #define PG8_MMA(ai, bj, At, Bt) do { __builtin_amdgcn_s_setprio(1); _Pragma("unroll") for (int m = 0; m < 4; ++m) _Pragma("unroll") for (int n = 0; n < 2; ++n) _Pragma("unroll") for (int k = 0; k < 2; ++k) \
;         acc[ai][bj][m][n] = __builtin_amdgcn_mfma_f32_16x16x32_bf16(Bt[n][k], At[m][k], acc[ai][bj][m][n], 0, 0, 0); __builtin_amdgcn_s_setprio(0); } while (0)
; #define PG8_WAIT_V(n) asm volatile("s_waitcnt vmcnt(" #n ")" ::: "memory")
; #define PG8_WAIT_L(n) asm volatile("s_waitcnt lgkmcnt(" #n ")" ::: "memory")
; #define PG8_BAR __builtin_amdgcn_s_barrier()
; #define PG8_SCHED __builtin_amdgcn_sched_barrier(0)
;     ...
;         for (int t = 0; t < nt; t += 2) {
;             const bool last = (t == nt - 2);
;             const char* a1 = cA + (size_t)(t + 1) * kstep;
;             const char* a2 = last ? nA : cA + (size_t)(t + 2) * kstep; const char* b2 = last ? nB : cB + (size_t)(t + 2) * kstep;
;             const char* a3 = a2 + kstep; const char* b3 = b2 + kstep;
;             PG8_LDB(B0, 0, 0); PG8_LDB(B1, 0, 1); PG8_SCHED; PG8_LDA(At, 0, 0); PG8_STAGE(PG8_SA(1, 1), a1 + hstepA, voffA);
;             PG8_WAIT_V(8); PG8_WAIT_L(0); PG8_BAR; PG8_MMA(0, 0, At, B0); PG8_MMA(0, 1, At, B1); PG8_BAR; PG8_SCHED;
;             PG8_LDA(At, 0, 1); PG8_STAGE(PG8_SB(0, 0), b2, voffB); PG8_STAGE(PG8_SB(0, 1), b2 + hstepB, voffB); PG8_STAGE(PG8_SA(0, 0), a2, voffA);
;             PG8_WAIT_V(8); PG8_WAIT_L(0); PG8_BAR; PG8_MMA(1, 0, At, B0); PG8_MMA(1, 1, At, B1); PG8_BAR; PG8_SCHED;
.LBB0_318:
	s_add_i32 s57, s38, 2
	s_add_u32 s19, s2, s0
	s_addc_u32 s27, s3, s1
	s_add_i32 s58, 0, 0x10000
	s_cmp_eq_u32 s51, s38
	s_cselect_b32 s39, s13, s27
	s_cselect_b32 s38, s56, s19
	s_cselect_b64 vcc, -1, 0
	s_add_i32 s19, 0, 0x14000
	v_lshl_add_u64 v[150:151], v[160:161], 0, s[0:1]
	v_add_u32_e32 v146, s58, v181
	s_waitcnt lgkmcnt(0)
	v_add_u32_e32 v178, s19, v181
	ds_read_b128 v[134:137], v146
	ds_read_b128 v[138:141], v146 offset:1024
	ds_read_b128 v[142:145], v146 offset:2048
	ds_read_b128 v[146:149], v146 offset:3072
	v_cndmask_b32_e32 v159, v151, v132, vcc
	v_cndmask_b32_e32 v158, v150, v133, vcc
	ds_read_b128 v[150:153], v178
	ds_read_b128 v[154:157], v178 offset:1024
	ds_read_b128 v[174:177], v178 offset:2048
	ds_read_b128 v[190:193], v178 offset:3072
	v_lshl_add_u64 v[178:179], s[2:3], 0, v[130:131]
	s_add_i32 m0, s11, 0xc000
	ds_read_b128 v[194:197], v188
	ds_read_b128 v[198:201], v188 offset:1024
	ds_read_b128 v[202:205], v188 offset:2048
	ds_read_b128 v[224:227], v188 offset:3072
	ds_read_b128 v[228:231], v188 offset:4096
	ds_read_b128 v[232:235], v188 offset:5120
	ds_read_b128 v[236:239], v188 offset:6144
	ds_read_b128 v[240:243], v188 offset:7168
	global_load_lds_dwordx4 v[178:179], off
	v_lshl_add_u64 v[178:179], s[2:3], 0, v[128:129]
	s_add_i32 m0, s11, 0xe000
	s_nop 0
	global_load_lds_dwordx4 v[178:179], off
	s_waitcnt vmcnt(8)
	s_waitcnt lgkmcnt(0)
	s_barrier
	s_setprio 1
	s_waitcnt lgkmcnt(0)
	v_mfma_f32_16x16x32_bf16 v[124:127], v[134:137], v[194:197], v[124:127]
	v_mfma_f32_16x16x32_bf16 v[120:123], v[142:145], v[194:197], v[120:123]
	v_mfma_f32_16x16x32_bf16 v[116:119], v[134:137], v[202:205], v[116:119]
	v_mfma_f32_16x16x32_bf16 v[112:115], v[142:145], v[202:205], v[112:115]
	v_mfma_f32_16x16x32_bf16 v[108:111], v[134:137], v[228:231], v[108:111]
	v_mfma_f32_16x16x32_bf16 v[104:107], v[142:145], v[228:231], v[104:107]
	v_mfma_f32_16x16x32_bf16 v[100:103], v[134:137], v[236:239], v[100:103]
	v_mfma_f32_16x16x32_bf16 v[96:99], v[142:145], v[236:239], v[96:99]
	v_mfma_f32_16x16x32_bf16 v[124:127], v[138:141], v[198:201], v[124:127]
	v_mfma_f32_16x16x32_bf16 v[120:123], v[146:149], v[198:201], v[120:123]
	v_mfma_f32_16x16x32_bf16 v[116:119], v[138:141], v[224:227], v[116:119]
	v_mfma_f32_16x16x32_bf16 v[112:115], v[146:149], v[224:227], v[112:115]
	v_mfma_f32_16x16x32_bf16 v[108:111], v[138:141], v[232:235], v[108:111]
	v_mfma_f32_16x16x32_bf16 v[104:107], v[146:149], v[232:235], v[104:107]
	v_mfma_f32_16x16x32_bf16 v[100:103], v[138:141], v[240:243], v[100:103]
	v_mfma_f32_16x16x32_bf16 v[96:99], v[146:149], v[240:243], v[96:99]
	v_mfma_f32_16x16x32_bf16 v[92:95], v[150:153], v[194:197], v[92:95]
	v_mfma_f32_16x16x32_bf16 v[88:91], v[174:177], v[194:197], v[88:91]
	v_mfma_f32_16x16x32_bf16 v[84:87], v[150:153], v[202:205], v[84:87]
	v_mfma_f32_16x16x32_bf16 v[80:83], v[174:177], v[202:205], v[80:83]
	v_mfma_f32_16x16x32_bf16 v[76:79], v[150:153], v[228:231], v[76:79]
	v_mfma_f32_16x16x32_bf16 v[72:75], v[174:177], v[228:231], v[72:75]
	v_mfma_f32_16x16x32_bf16 v[68:71], v[150:153], v[236:239], v[68:71]
	v_mfma_f32_16x16x32_bf16 v[64:67], v[174:177], v[236:239], v[64:67]
	v_mfma_f32_16x16x32_bf16 v[92:95], v[154:157], v[198:201], v[92:95]
	v_mfma_f32_16x16x32_bf16 v[88:91], v[190:193], v[198:201], v[88:91]
	v_mfma_f32_16x16x32_bf16 v[84:87], v[154:157], v[224:227], v[84:87]
	v_mfma_f32_16x16x32_bf16 v[80:83], v[190:193], v[224:227], v[80:83]
	v_mfma_f32_16x16x32_bf16 v[76:79], v[154:157], v[232:235], v[76:79]
	v_mfma_f32_16x16x32_bf16 v[72:75], v[190:193], v[232:235], v[72:75]
	v_mfma_f32_16x16x32_bf16 v[68:71], v[154:157], v[240:243], v[68:71]
	v_mfma_f32_16x16x32_bf16 v[64:67], v[190:193], v[240:243], v[64:67]
	s_setprio 0
	s_barrier
	s_add_i32 s27, s58, s10
	v_lshl_add_u64 v[178:179], v[158:159], 0, v[164:165]
	s_mov_b32 m0, s27
	ds_read_b128 v[194:197], v188 offset:16384
	ds_read_b128 v[198:201], v188 offset:17408
	ds_read_b128 v[202:205], v188 offset:18432
	ds_read_b128 v[224:227], v188 offset:19456
	ds_read_b128 v[228:231], v188 offset:20480
	ds_read_b128 v[232:235], v188 offset:21504
	ds_read_b128 v[236:239], v188 offset:22528
	ds_read_b128 v[240:243], v188 offset:23552
	global_load_lds_dwordx4 v[178:179], off
	v_lshl_add_u64 v[212:213], v[158:159], 0, v[168:169]
	s_add_i32 m0, s27, 0x2000
	v_lshl_add_u64 v[158:159], v[158:159], 0, s[96:97]
	s_add_i32 s19, s19, s10
	global_load_lds_dwordx4 v[212:213], off
	v_lshl_add_u64 v[218:219], v[158:159], 0, v[164:165]
	s_mov_b32 m0, s19
	v_lshl_add_u64 v[158:159], v[158:159], 0, v[168:169]
	global_load_lds_dwordx4 v[218:219], off
	s_add_i32 m0, s19, 0x2000
	v_lshl_add_u64 v[244:245], s[38:39], 0, v[162:163]
	global_load_lds_dwordx4 v[158:159], off
	s_mov_b32 m0, s11
	v_lshl_add_u64 v[246:247], s[38:39], 0, v[166:167]
	global_load_lds_dwordx4 v[244:245], off
	s_mov_b32 m0, s20
	s_nop 0
	global_load_lds_dwordx4 v[246:247], off
	s_waitcnt vmcnt(8)
	s_waitcnt lgkmcnt(0)
	s_barrier
; #define PG8_STAGE(bufoff, gbase, voff) do { _Pragma("unroll") for (int _i = 0; _i < 2; ++_i) \
;         __builtin_amdgcn_global_load_lds((const unsigned*)((const char*)(gbase) + (voff)[_i]), (LAS unsigned*)(lds + (bufoff) + ldsw + _i * 8192), 16, 0, 0); } while (0)
; #define PG8_LDA(dst, b, h) do { _Pragma("unroll") for (int m = 0; m < 4; ++m) _Pragma("unroll") for (int k = 0; k < 2; ++k) dst[m][k] = *(const LAS bf16x8*)(lds + PG8_SA(b, h) + aoff + m * 2048 + k * 1024); } while (0)
; #define PG8_LDB(dst, b, h) do { _Pragma("unroll") for (int n = 0; n < 2; ++n) _Pragma("unroll") for (int k = 0; k < 2; ++k) dst[n][k] = *(const LAS bf16x8*)(lds + PG8_SB(b, h) + boff + n * 2048 + k * 1024); } while (0)
; #define PG8_MMA(ai, bj, At, Bt) do { __builtin_amdgcn_s_setprio(1); _Pragma("unroll") for (int m = 0; m < 4; ++m) _Pragma("unroll") for (int n = 0; n < 2; ++n) _Pragma("unroll") for (int k = 0; k < 2; ++k) \
;         acc[ai][bj][m][n] = __builtin_amdgcn_mfma_f32_16x16x32_bf16(Bt[n][k], At[m][k], acc[ai][bj][m][n], 0, 0, 0); __builtin_amdgcn_s_setprio(0); } while (0)
; #define PG8_WAIT_V(n) asm volatile("s_waitcnt vmcnt(" #n ")" ::: "memory")
; #define PG8_WAIT_L(n) asm volatile("s_waitcnt lgkmcnt(" #n ")" ::: "memory")
; #define PG8_BAR __builtin_amdgcn_s_barrier()
; #define PG8_SCHED __builtin_amdgcn_sched_barrier(0)
;     ...
;             PG8_WAIT_V(8); PG8_WAIT_L(0); PG8_BAR; PG8_MMA(1, 0, At, B0); PG8_MMA(1, 1, At, B1); PG8_BAR; PG8_SCHED;
;             PG8_LDB(B0, 1, 0); PG8_LDB(B1, 1, 1); PG8_SCHED; PG8_LDA(At, 1, 0); PG8_STAGE(PG8_SA(0, 1), a2 + hstepA, voffA);
;             PG8_WAIT_V(8); PG8_WAIT_L(0); PG8_BAR; PG8_MMA(0, 0, At, B0); PG8_MMA(0, 1, At, B1); PG8_BAR; PG8_SCHED;
	s_setprio 1
	s_waitcnt lgkmcnt(0)
	v_mfma_f32_16x16x32_bf16 v[60:63], v[134:137], v[194:197], v[60:63]
	v_mfma_f32_16x16x32_bf16 v[56:59], v[142:145], v[194:197], v[56:59]
	v_mfma_f32_16x16x32_bf16 v[52:55], v[134:137], v[202:205], v[52:55]
	v_mfma_f32_16x16x32_bf16 v[48:51], v[142:145], v[202:205], v[48:51]
	v_mfma_f32_16x16x32_bf16 v[44:47], v[134:137], v[228:231], v[44:47]
	v_mfma_f32_16x16x32_bf16 v[40:43], v[142:145], v[228:231], v[40:43]
	v_mfma_f32_16x16x32_bf16 v[36:39], v[134:137], v[236:239], v[36:39]
	v_mfma_f32_16x16x32_bf16 v[32:35], v[142:145], v[236:239], v[32:35]
	v_mfma_f32_16x16x32_bf16 v[60:63], v[138:141], v[198:201], v[60:63]
	v_mfma_f32_16x16x32_bf16 v[56:59], v[146:149], v[198:201], v[56:59]
	v_mfma_f32_16x16x32_bf16 v[52:55], v[138:141], v[224:227], v[52:55]
	v_mfma_f32_16x16x32_bf16 v[48:51], v[146:149], v[224:227], v[48:51]
	v_mfma_f32_16x16x32_bf16 v[44:47], v[138:141], v[232:235], v[44:47]
	v_mfma_f32_16x16x32_bf16 v[40:43], v[146:149], v[232:235], v[40:43]
	v_mfma_f32_16x16x32_bf16 v[36:39], v[138:141], v[240:243], v[36:39]
	v_mfma_f32_16x16x32_bf16 v[32:35], v[146:149], v[240:243], v[32:35]
	v_mfma_f32_16x16x32_bf16 v[28:31], v[150:153], v[194:197], v[28:31]
	v_mfma_f32_16x16x32_bf16 v[24:27], v[174:177], v[194:197], v[24:27]
	v_mfma_f32_16x16x32_bf16 v[20:23], v[150:153], v[202:205], v[20:23]
	v_mfma_f32_16x16x32_bf16 v[16:19], v[174:177], v[202:205], v[16:19]
	v_mfma_f32_16x16x32_bf16 v[12:15], v[150:153], v[228:231], v[12:15]
	v_mfma_f32_16x16x32_bf16 v[8:11], v[174:177], v[228:231], v[8:11]
	v_mfma_f32_16x16x32_bf16 v[4:7], v[150:153], v[236:239], v[4:7]
	v_mfma_f32_16x16x32_bf16 v[0:3], v[174:177], v[236:239], v[0:3]
	v_mfma_f32_16x16x32_bf16 v[28:31], v[154:157], v[198:201], v[28:31]
	v_mfma_f32_16x16x32_bf16 v[24:27], v[190:193], v[198:201], v[24:27]
	v_mfma_f32_16x16x32_bf16 v[20:23], v[154:157], v[224:227], v[20:23]
	v_mfma_f32_16x16x32_bf16 v[16:19], v[190:193], v[224:227], v[16:19]
	v_mfma_f32_16x16x32_bf16 v[12:15], v[154:157], v[232:235], v[12:15]
	v_mfma_f32_16x16x32_bf16 v[8:11], v[190:193], v[232:235], v[8:11]
	v_mfma_f32_16x16x32_bf16 v[4:7], v[154:157], v[240:243], v[4:7]
	v_mfma_f32_16x16x32_bf16 v[0:3], v[190:193], v[240:243], v[0:3]
	s_setprio 0
	s_barrier
	s_add_i32 s19, 0, 0x18000
	s_add_i32 s27, 0, 0x1c000
	v_add_u32_e32 v146, s19, v181
	v_add_u32_e32 v182, s27, v181
	ds_read_b128 v[134:137], v146
	ds_read_b128 v[138:141], v146 offset:1024
	ds_read_b128 v[142:145], v146 offset:2048
	ds_read_b128 v[146:149], v146 offset:3072
	ds_read_b128 v[150:153], v182
	ds_read_b128 v[154:157], v182 offset:1024
	ds_read_b128 v[174:177], v182 offset:2048
	ds_read_b128 v[190:193], v182 offset:3072
	s_add_u32 s38, s38, s96
	s_addc_u32 s39, s39, 0
	s_mov_b32 m0, s48
	v_lshl_add_u64 v[248:249], s[38:39], 0, v[162:163]
	ds_read_b128 v[194:197], v188 offset:32768
	ds_read_b128 v[198:201], v188 offset:33792
	ds_read_b128 v[202:205], v188 offset:34816
	ds_read_b128 v[224:227], v188 offset:35840
	ds_read_b128 v[228:231], v188 offset:36864
	ds_read_b128 v[232:235], v188 offset:37888
	ds_read_b128 v[236:239], v188 offset:38912
	ds_read_b128 v[240:243], v188 offset:39936
	global_load_lds_dwordx4 v[248:249], off
	v_lshl_add_u64 v[248:249], s[38:39], 0, v[166:167]
	s_mov_b32 m0, s49
	s_nop 0
	global_load_lds_dwordx4 v[248:249], off
	s_waitcnt vmcnt(8)
	s_waitcnt lgkmcnt(0)
	s_barrier
	s_setprio 1
	s_waitcnt lgkmcnt(0)
	v_mfma_f32_16x16x32_bf16 v[124:127], v[134:137], v[194:197], v[124:127]
	v_mfma_f32_16x16x32_bf16 v[120:123], v[142:145], v[194:197], v[120:123]
	v_mfma_f32_16x16x32_bf16 v[116:119], v[134:137], v[202:205], v[116:119]
	v_mfma_f32_16x16x32_bf16 v[112:115], v[142:145], v[202:205], v[112:115]
	v_mfma_f32_16x16x32_bf16 v[108:111], v[134:137], v[228:231], v[108:111]
	v_mfma_f32_16x16x32_bf16 v[104:107], v[142:145], v[228:231], v[104:107]
	v_mfma_f32_16x16x32_bf16 v[100:103], v[134:137], v[236:239], v[100:103]
	v_mfma_f32_16x16x32_bf16 v[96:99], v[142:145], v[236:239], v[96:99]
	v_mfma_f32_16x16x32_bf16 v[124:127], v[138:141], v[198:201], v[124:127]
	v_mfma_f32_16x16x32_bf16 v[120:123], v[146:149], v[198:201], v[120:123]
	v_mfma_f32_16x16x32_bf16 v[116:119], v[138:141], v[224:227], v[116:119]
	v_mfma_f32_16x16x32_bf16 v[112:115], v[146:149], v[224:227], v[112:115]
	v_mfma_f32_16x16x32_bf16 v[108:111], v[138:141], v[232:235], v[108:111]
	v_mfma_f32_16x16x32_bf16 v[104:107], v[146:149], v[232:235], v[104:107]
	v_mfma_f32_16x16x32_bf16 v[100:103], v[138:141], v[240:243], v[100:103]
	v_mfma_f32_16x16x32_bf16 v[96:99], v[146:149], v[240:243], v[96:99]
	v_mfma_f32_16x16x32_bf16 v[92:95], v[150:153], v[194:197], v[92:95]
	v_mfma_f32_16x16x32_bf16 v[88:91], v[174:177], v[194:197], v[88:91]
	v_mfma_f32_16x16x32_bf16 v[84:87], v[150:153], v[202:205], v[84:87]
	v_mfma_f32_16x16x32_bf16 v[80:83], v[174:177], v[202:205], v[80:83]
	v_mfma_f32_16x16x32_bf16 v[76:79], v[150:153], v[228:231], v[76:79]
	v_mfma_f32_16x16x32_bf16 v[72:75], v[174:177], v[228:231], v[72:75]
	v_mfma_f32_16x16x32_bf16 v[68:71], v[150:153], v[236:239], v[68:71]
	v_mfma_f32_16x16x32_bf16 v[64:67], v[174:177], v[236:239], v[64:67]
	v_mfma_f32_16x16x32_bf16 v[92:95], v[154:157], v[198:201], v[92:95]
	v_mfma_f32_16x16x32_bf16 v[88:91], v[190:193], v[198:201], v[88:91]
	v_mfma_f32_16x16x32_bf16 v[84:87], v[154:157], v[224:227], v[84:87]
	v_mfma_f32_16x16x32_bf16 v[80:83], v[190:193], v[224:227], v[80:83]
	v_mfma_f32_16x16x32_bf16 v[76:79], v[154:157], v[232:235], v[76:79]
	v_mfma_f32_16x16x32_bf16 v[72:75], v[190:193], v[232:235], v[72:75]
	v_mfma_f32_16x16x32_bf16 v[68:71], v[154:157], v[240:243], v[68:71]
	v_mfma_f32_16x16x32_bf16 v[64:67], v[190:193], v[240:243], v[64:67]
	s_setprio 0
	s_barrier
; #define PG8_STAGE(bufoff, gbase, voff) do { _Pragma("unroll") for (int _i = 0; _i < 2; ++_i) \
;         __builtin_amdgcn_global_load_lds((const unsigned*)((const char*)(gbase) + (voff)[_i]), (LAS unsigned*)(lds + (bufoff) + ldsw + _i * 8192), 16, 0, 0); } while (0)
; #define PG8_LDA(dst, b, h) do { _Pragma("unroll") for (int m = 0; m < 4; ++m) _Pragma("unroll") for (int k = 0; k < 2; ++k) dst[m][k] = *(const LAS bf16x8*)(lds + PG8_SA(b, h) + aoff + m * 2048 + k * 1024); } while (0)
; #define PG8_MMA(ai, bj, At, Bt) do { __builtin_amdgcn_s_setprio(1); _Pragma("unroll") for (int m = 0; m < 4; ++m) _Pragma("unroll") for (int n = 0; n < 2; ++n) _Pragma("unroll") for (int k = 0; k < 2; ++k) \
;         acc[ai][bj][m][n] = __builtin_amdgcn_mfma_f32_16x16x32_bf16(Bt[n][k], At[m][k], acc[ai][bj][m][n], 0, 0, 0); __builtin_amdgcn_s_setprio(0); } while (0)
; #define PG8_WAIT_V(n) asm volatile("s_waitcnt vmcnt(" #n ")" ::: "memory")
; #define PG8_WAIT_L(n) asm volatile("s_waitcnt lgkmcnt(" #n ")" ::: "memory")
; #define PG8_BAR __builtin_amdgcn_s_barrier()
; #define PG8_SCHED __builtin_amdgcn_sched_barrier(0)
;     ...
;             PG8_LDA(At, 1, 1); PG8_STAGE(PG8_SB(1, 0), b3, voffB); PG8_STAGE(PG8_SB(1, 1), b3 + hstepB, voffB); PG8_STAGE(PG8_SA(1, 0), a3, voffA);
;             PG8_WAIT_V(8); PG8_WAIT_L(0); PG8_BAR; PG8_MMA(1, 0, At, B0); PG8_MMA(1, 1, At, B1); PG8_BAR; PG8_SCHED;
;         }
;         if (wr == 0) PG8_BAR;
	s_add_i32 s19, s19, s10
	v_lshl_add_u64 v[178:179], v[178:179], 0, s[70:71]
	s_mov_b32 m0, s19
	ds_read_b128 v[194:197], v188 offset:49152
	ds_read_b128 v[198:201], v188 offset:50176
	ds_read_b128 v[202:205], v188 offset:51200
	ds_read_b128 v[224:227], v188 offset:52224
	ds_read_b128 v[228:231], v188 offset:53248
	ds_read_b128 v[232:235], v188 offset:54272
	ds_read_b128 v[236:239], v188 offset:55296
	ds_read_b128 v[240:243], v188 offset:56320
	global_load_lds_dwordx4 v[178:179], off
	v_lshl_add_u64 v[178:179], v[212:213], 0, s[70:71]
	s_add_i32 m0, s19, 0x2000
	s_add_i32 s19, s27, s10
	global_load_lds_dwordx4 v[178:179], off
	v_lshl_add_u64 v[178:179], v[218:219], 0, s[70:71]
	s_mov_b32 m0, s19
	v_lshl_add_u64 v[158:159], v[158:159], 0, s[70:71]
	global_load_lds_dwordx4 v[178:179], off
	s_add_i32 m0, s19, 0x2000
	s_nop 0
	global_load_lds_dwordx4 v[158:159], off
	v_lshl_add_u64 v[158:159], v[244:245], 0, s[70:71]
	s_mov_b32 m0, s62
	s_nop 0
	global_load_lds_dwordx4 v[158:159], off
	v_lshl_add_u64 v[158:159], v[246:247], 0, s[70:71]
	s_mov_b32 m0, s63
	s_nop 0
	global_load_lds_dwordx4 v[158:159], off
	s_waitcnt vmcnt(8)
	s_waitcnt lgkmcnt(0)
	s_barrier
	s_setprio 1
	s_waitcnt lgkmcnt(0)
	v_mfma_f32_16x16x32_bf16 v[60:63], v[134:137], v[194:197], v[60:63]
	v_mfma_f32_16x16x32_bf16 v[56:59], v[142:145], v[194:197], v[56:59]
	v_mfma_f32_16x16x32_bf16 v[52:55], v[134:137], v[202:205], v[52:55]
	v_mfma_f32_16x16x32_bf16 v[48:51], v[142:145], v[202:205], v[48:51]
	v_mfma_f32_16x16x32_bf16 v[44:47], v[134:137], v[228:231], v[44:47]
	v_mfma_f32_16x16x32_bf16 v[40:43], v[142:145], v[228:231], v[40:43]
	v_mfma_f32_16x16x32_bf16 v[36:39], v[134:137], v[236:239], v[36:39]
	v_mfma_f32_16x16x32_bf16 v[32:35], v[142:145], v[236:239], v[32:35]
	v_mfma_f32_16x16x32_bf16 v[60:63], v[138:141], v[198:201], v[60:63]
	v_mfma_f32_16x16x32_bf16 v[56:59], v[146:149], v[198:201], v[56:59]
	v_mfma_f32_16x16x32_bf16 v[52:55], v[138:141], v[224:227], v[52:55]
	v_mfma_f32_16x16x32_bf16 v[48:51], v[146:149], v[224:227], v[48:51]
	v_mfma_f32_16x16x32_bf16 v[44:47], v[138:141], v[232:235], v[44:47]
	v_mfma_f32_16x16x32_bf16 v[40:43], v[146:149], v[232:235], v[40:43]
	v_mfma_f32_16x16x32_bf16 v[36:39], v[138:141], v[240:243], v[36:39]
	v_mfma_f32_16x16x32_bf16 v[32:35], v[146:149], v[240:243], v[32:35]
	v_mfma_f32_16x16x32_bf16 v[28:31], v[150:153], v[194:197], v[28:31]
	v_mfma_f32_16x16x32_bf16 v[24:27], v[174:177], v[194:197], v[24:27]
	v_mfma_f32_16x16x32_bf16 v[20:23], v[150:153], v[202:205], v[20:23]
	v_mfma_f32_16x16x32_bf16 v[16:19], v[174:177], v[202:205], v[16:19]
	v_mfma_f32_16x16x32_bf16 v[12:15], v[150:153], v[228:231], v[12:15]
	v_mfma_f32_16x16x32_bf16 v[8:11], v[174:177], v[228:231], v[8:11]
	v_mfma_f32_16x16x32_bf16 v[4:7], v[150:153], v[236:239], v[4:7]
	v_mfma_f32_16x16x32_bf16 v[0:3], v[174:177], v[236:239], v[0:3]
	v_mfma_f32_16x16x32_bf16 v[28:31], v[154:157], v[198:201], v[28:31]
	v_mfma_f32_16x16x32_bf16 v[24:27], v[190:193], v[198:201], v[24:27]
	v_mfma_f32_16x16x32_bf16 v[20:23], v[154:157], v[224:227], v[20:23]
	v_mfma_f32_16x16x32_bf16 v[16:19], v[190:193], v[224:227], v[16:19]
	v_mfma_f32_16x16x32_bf16 v[12:15], v[154:157], v[232:235], v[12:15]
	v_mfma_f32_16x16x32_bf16 v[8:11], v[190:193], v[232:235], v[8:11]
	v_mfma_f32_16x16x32_bf16 v[4:7], v[154:157], v[240:243], v[4:7]
	v_mfma_f32_16x16x32_bf16 v[0:3], v[190:193], v[240:243], v[0:3]
	s_setprio 0
	s_barrier
	s_add_u32 s0, s0, 0x100
	s_addc_u32 s1, s1, 0
	v_lshl_add_u64 v[130:131], v[130:131], 0, s[94:95]
	v_lshl_add_u64 v[128:129], v[128:129], 0, s[94:95]
	s_cmp_ge_u32 s57, s16
	s_mov_b32 s38, s57
	s_cbranch_scc0 .LBB0_318
	v_readlane_b32 s0, v254, 50
	v_readlane_b32 s1, v254, 51
	s_and_b64 vcc, exec, s[0:1]
	s_mov_b32 s68, 0x134000
	s_mov_b32 s69, 0x160000
	s_cbranch_vccz .LBB0_321
	s_barrier

; #define PG8_STAGE(bufoff, gbase, voff) do { _Pragma("unroll") for (int _i = 0; _i < 2; ++_i) \
;         __builtin_amdgcn_global_load_lds((const unsigned*)((const char*)(gbase) + (voff)[_i]), (LAS unsigned*)(lds + (bufoff) + ldsw + _i * 8192), 16, 0, 0); } while (0)
; #define PG8_LDA(dst, b, h) do { _Pragma("unroll") for (int m = 0; m < 4; ++m) _Pragma("unroll") for (int k = 0; k < 2; ++k) dst[m][k] = *(const LAS bf16x8*)(lds + PG8_SA(b, h) + aoff + m * 2048 + k * 1024); } while (0)
; #define PG8_LDB(dst, b, h) do { _Pragma("unroll") for (int n = 0; n < 2; ++n) _Pragma("unroll") for (int k = 0; k < 2; ++k) dst[n][k] = *(const LAS bf16x8*)(lds + PG8_SB(b, h) + boff + n * 2048 + k * 1024); } while (0)
; #define PG8_MMA(ai, bj, At, Bt) do { __builtin_amdgcn_s_setprio(1); _Pragma("unroll") for (int m = 0; m < 4; ++m) _Pragma("unroll") for (int n = 0; n < 2; ++n) _Pragma("unroll") for (int k = 0; k < 2; ++k) \
;         acc[ai][bj][m][n] = __builtin_amdgcn_mfma_f32_16x16x32_bf16(Bt[n][k], At[m][k], acc[ai][bj][m][n], 0, 0, 0); __builtin_amdgcn_s_setprio(0); } while (0)
; #define PG8_WAIT_V(n) asm volatile("s_waitcnt vmcnt(" #n ")" ::: "memory")
; #define PG8_WAIT_L(n) asm volatile("s_waitcnt lgkmcnt(" #n ")" ::: "memory")
; #define PG8_BAR __builtin_amdgcn_s_barrier()
; #define PG8_SCHED __builtin_amdgcn_sched_barrier(0)
;     ...
;         for (int t = 0; t < nt; t += 2) {
;             const bool last = (t == nt - 2);
;             const char* a1 = cA + (size_t)(t + 1) * kstep;
;             const char* a2 = last ? nA : cA + (size_t)(t + 2) * kstep; const char* b2 = last ? nB : cB + (size_t)(t + 2) * kstep;
;             const char* a3 = a2 + kstep; const char* b3 = b2 + kstep;
;             PG8_LDB(B0, 0, 0); PG8_LDB(B1, 0, 1); PG8_SCHED; PG8_LDA(At, 0, 0); PG8_STAGE(PG8_SA(1, 1), a1 + hstepA, voffA);
;             PG8_WAIT_V(8); PG8_WAIT_L(0); PG8_BAR; PG8_MMA(0, 0, At, B0); PG8_MMA(0, 1, At, B1); PG8_BAR; PG8_SCHED;
;             PG8_LDA(At, 0, 1); PG8_STAGE(PG8_SB(0, 0), b2, voffB); PG8_STAGE(PG8_SB(0, 1), b2 + hstepB, voffB); PG8_STAGE(PG8_SA(0, 0), a2, voffA);
;             PG8_WAIT_V(8); PG8_WAIT_L(0); PG8_BAR; PG8_MMA(1, 0, At, B0); PG8_MMA(1, 1, At, B1); PG8_BAR; PG8_SCHED;
.LBB0_416:
	s_add_i32 s8, s2, 2
	s_add_u32 s9, s52, s0
	s_addc_u32 s3, s53, s1
	s_add_i32 s26, 0, 0x10000
	s_cmp_eq_u32 s65, s2
	s_cselect_b32 s3, s6, s3
	s_cselect_b32 s2, s7, s9
	v_add_u32_e32 v153, s26, v148
	s_cselect_b64 vcc, -1, 0
	s_add_i32 s9, 0, 0x14000
	v_lshl_add_u64 v[170:171], v[128:129], 0, s[0:1]
	ds_read_b128 v[154:157], v153
	ds_read_b128 v[158:161], v153 offset:1024
	ds_read_b128 v[162:165], v153 offset:2048
	ds_read_b128 v[166:169], v153 offset:3072
	v_add_u32_e32 v153, s9, v148
	v_cndmask_b32_e32 v205, v171, v151, vcc
	v_cndmask_b32_e32 v204, v170, v152, vcc
	ds_read_b128 v[170:173], v153
	ds_read_b128 v[174:177], v153 offset:1024
	ds_read_b128 v[178:181], v153 offset:2048
	ds_read_b128 v[188:191], v153 offset:3072
	v_lshl_add_u64 v[244:245], s[52:53], 0, v[146:147]
	s_add_i32 m0, s41, 0xc000
	ds_read_b128 v[192:195], v149
	ds_read_b128 v[196:199], v149 offset:1024
	ds_read_b128 v[200:203], v149 offset:2048
	ds_read_b128 v[224:227], v149 offset:3072
	ds_read_b128 v[228:231], v149 offset:4096
	ds_read_b128 v[232:235], v149 offset:5120
	ds_read_b128 v[236:239], v149 offset:6144
	ds_read_b128 v[240:243], v149 offset:7168
	global_load_lds_dwordx4 v[244:245], off
	v_lshl_add_u64 v[244:245], s[52:53], 0, v[144:145]
	s_add_i32 m0, s41, 0xe000
	s_nop 0
	global_load_lds_dwordx4 v[244:245], off
	s_waitcnt vmcnt(8)
	s_waitcnt lgkmcnt(0)
	s_barrier
	s_setprio 1
	s_waitcnt lgkmcnt(0)
	v_mfma_f32_16x16x32_bf16 v[124:127], v[154:157], v[192:195], v[124:127]
	v_mfma_f32_16x16x32_bf16 v[120:123], v[162:165], v[192:195], v[120:123]
	v_mfma_f32_16x16x32_bf16 v[116:119], v[154:157], v[200:203], v[116:119]
	v_mfma_f32_16x16x32_bf16 v[112:115], v[162:165], v[200:203], v[112:115]
	v_mfma_f32_16x16x32_bf16 v[108:111], v[154:157], v[228:231], v[108:111]
	v_mfma_f32_16x16x32_bf16 v[104:107], v[162:165], v[228:231], v[104:107]
	v_mfma_f32_16x16x32_bf16 v[100:103], v[154:157], v[236:239], v[100:103]
	v_mfma_f32_16x16x32_bf16 v[96:99], v[162:165], v[236:239], v[96:99]
	v_mfma_f32_16x16x32_bf16 v[124:127], v[158:161], v[196:199], v[124:127]
	v_mfma_f32_16x16x32_bf16 v[120:123], v[166:169], v[196:199], v[120:123]
	v_mfma_f32_16x16x32_bf16 v[116:119], v[158:161], v[224:227], v[116:119]
	v_mfma_f32_16x16x32_bf16 v[112:115], v[166:169], v[224:227], v[112:115]
	v_mfma_f32_16x16x32_bf16 v[108:111], v[158:161], v[232:235], v[108:111]
	v_mfma_f32_16x16x32_bf16 v[104:107], v[166:169], v[232:235], v[104:107]
	v_mfma_f32_16x16x32_bf16 v[100:103], v[158:161], v[240:243], v[100:103]
	v_mfma_f32_16x16x32_bf16 v[96:99], v[166:169], v[240:243], v[96:99]
	v_mfma_f32_16x16x32_bf16 v[92:95], v[170:173], v[192:195], v[92:95]
	v_mfma_f32_16x16x32_bf16 v[88:91], v[178:181], v[192:195], v[88:91]
	v_mfma_f32_16x16x32_bf16 v[84:87], v[170:173], v[200:203], v[84:87]
	v_mfma_f32_16x16x32_bf16 v[80:83], v[178:181], v[200:203], v[80:83]
	v_mfma_f32_16x16x32_bf16 v[76:79], v[170:173], v[228:231], v[76:79]
	v_mfma_f32_16x16x32_bf16 v[72:75], v[178:181], v[228:231], v[72:75]
	v_mfma_f32_16x16x32_bf16 v[68:71], v[170:173], v[236:239], v[68:71]
	v_mfma_f32_16x16x32_bf16 v[64:67], v[178:181], v[236:239], v[64:67]
	v_mfma_f32_16x16x32_bf16 v[92:95], v[174:177], v[196:199], v[92:95]
	v_mfma_f32_16x16x32_bf16 v[88:91], v[188:191], v[196:199], v[88:91]
	v_mfma_f32_16x16x32_bf16 v[84:87], v[174:177], v[224:227], v[84:87]
	v_mfma_f32_16x16x32_bf16 v[80:83], v[188:191], v[224:227], v[80:83]
	v_mfma_f32_16x16x32_bf16 v[76:79], v[174:177], v[232:235], v[76:79]
	v_mfma_f32_16x16x32_bf16 v[72:75], v[188:191], v[232:235], v[72:75]
	v_mfma_f32_16x16x32_bf16 v[68:71], v[174:177], v[240:243], v[68:71]
	v_mfma_f32_16x16x32_bf16 v[64:67], v[188:191], v[240:243], v[64:67]
	s_setprio 0
	s_barrier
	s_add_i32 s26, s26, s40
	v_lshl_add_u64 v[244:245], v[204:205], 0, v[132:133]
	s_mov_b32 m0, s26
	ds_read_b128 v[192:195], v149 offset:16384
	ds_read_b128 v[196:199], v149 offset:17408
	ds_read_b128 v[200:203], v149 offset:18432
	ds_read_b128 v[224:227], v149 offset:19456
	ds_read_b128 v[228:231], v149 offset:20480
	ds_read_b128 v[232:235], v149 offset:21504
	ds_read_b128 v[236:239], v149 offset:22528
	ds_read_b128 v[240:243], v149 offset:23552
	global_load_lds_dwordx4 v[244:245], off
	v_lshl_add_u64 v[246:247], v[204:205], 0, v[136:137]
	s_add_i32 m0, s26, 0x2000
	v_lshl_add_u64 v[204:205], v[204:205], 0, s[58:59]
	s_add_i32 s9, s9, s40
	global_load_lds_dwordx4 v[246:247], off
	v_lshl_add_u64 v[248:249], v[204:205], 0, v[132:133]
	s_mov_b32 m0, s9
	v_lshl_add_u64 v[204:205], v[204:205], 0, v[136:137]
	global_load_lds_dwordx4 v[248:249], off
	s_add_i32 m0, s9, 0x2000
	v_lshl_add_u64 v[250:251], s[2:3], 0, v[130:131]
	global_load_lds_dwordx4 v[204:205], off
	s_mov_b32 m0, s41
	v_lshl_add_u64 v[218:219], s[2:3], 0, v[134:135]
	global_load_lds_dwordx4 v[250:251], off
	s_mov_b32 m0, s49
	s_nop 0
	global_load_lds_dwordx4 v[218:219], off
	s_waitcnt vmcnt(8)
	s_waitcnt lgkmcnt(0)
	s_barrier
; #define PG8_STAGE(bufoff, gbase, voff) do { _Pragma("unroll") for (int _i = 0; _i < 2; ++_i) \
;         __builtin_amdgcn_global_load_lds((const unsigned*)((const char*)(gbase) + (voff)[_i]), (LAS unsigned*)(lds + (bufoff) + ldsw + _i * 8192), 16, 0, 0); } while (0)
; #define PG8_LDA(dst, b, h) do { _Pragma("unroll") for (int m = 0; m < 4; ++m) _Pragma("unroll") for (int k = 0; k < 2; ++k) dst[m][k] = *(const LAS bf16x8*)(lds + PG8_SA(b, h) + aoff + m * 2048 + k * 1024); } while (0)
; #define PG8_LDB(dst, b, h) do { _Pragma("unroll") for (int n = 0; n < 2; ++n) _Pragma("unroll") for (int k = 0; k < 2; ++k) dst[n][k] = *(const LAS bf16x8*)(lds + PG8_SB(b, h) + boff + n * 2048 + k * 1024); } while (0)
; #define PG8_MMA(ai, bj, At, Bt) do { __builtin_amdgcn_s_setprio(1); _Pragma("unroll") for (int m = 0; m < 4; ++m) _Pragma("unroll") for (int n = 0; n < 2; ++n) _Pragma("unroll") for (int k = 0; k < 2; ++k) \
;         acc[ai][bj][m][n] = __builtin_amdgcn_mfma_f32_16x16x32_bf16(Bt[n][k], At[m][k], acc[ai][bj][m][n], 0, 0, 0); __builtin_amdgcn_s_setprio(0); } while (0)
; #define PG8_WAIT_V(n) asm volatile("s_waitcnt vmcnt(" #n ")" ::: "memory")
; #define PG8_WAIT_L(n) asm volatile("s_waitcnt lgkmcnt(" #n ")" ::: "memory")
; #define PG8_BAR __builtin_amdgcn_s_barrier()
; #define PG8_SCHED __builtin_amdgcn_sched_barrier(0)
;     ...
;             PG8_WAIT_V(8); PG8_WAIT_L(0); PG8_BAR; PG8_MMA(1, 0, At, B0); PG8_MMA(1, 1, At, B1); PG8_BAR; PG8_SCHED;
;             PG8_LDB(B0, 1, 0); PG8_LDB(B1, 1, 1); PG8_SCHED; PG8_LDA(At, 1, 0); PG8_STAGE(PG8_SA(0, 1), a2 + hstepA, voffA);
;             PG8_WAIT_V(8); PG8_WAIT_L(0); PG8_BAR; PG8_MMA(0, 0, At, B0); PG8_MMA(0, 1, At, B1); PG8_BAR; PG8_SCHED;
	s_setprio 1
	s_waitcnt lgkmcnt(0)
	v_mfma_f32_16x16x32_bf16 v[60:63], v[154:157], v[192:195], v[60:63]
	v_mfma_f32_16x16x32_bf16 v[56:59], v[162:165], v[192:195], v[56:59]
	v_mfma_f32_16x16x32_bf16 v[52:55], v[154:157], v[200:203], v[52:55]
	v_mfma_f32_16x16x32_bf16 v[48:51], v[162:165], v[200:203], v[48:51]
	v_mfma_f32_16x16x32_bf16 v[44:47], v[154:157], v[228:231], v[44:47]
	v_mfma_f32_16x16x32_bf16 v[40:43], v[162:165], v[228:231], v[40:43]
	v_mfma_f32_16x16x32_bf16 v[36:39], v[154:157], v[236:239], v[36:39]
	v_mfma_f32_16x16x32_bf16 v[32:35], v[162:165], v[236:239], v[32:35]
	v_mfma_f32_16x16x32_bf16 v[60:63], v[158:161], v[196:199], v[60:63]
	v_mfma_f32_16x16x32_bf16 v[56:59], v[166:169], v[196:199], v[56:59]
	v_mfma_f32_16x16x32_bf16 v[52:55], v[158:161], v[224:227], v[52:55]
	v_mfma_f32_16x16x32_bf16 v[48:51], v[166:169], v[224:227], v[48:51]
	v_mfma_f32_16x16x32_bf16 v[44:47], v[158:161], v[232:235], v[44:47]
	v_mfma_f32_16x16x32_bf16 v[40:43], v[166:169], v[232:235], v[40:43]
	v_mfma_f32_16x16x32_bf16 v[36:39], v[158:161], v[240:243], v[36:39]
	v_mfma_f32_16x16x32_bf16 v[32:35], v[166:169], v[240:243], v[32:35]
	v_mfma_f32_16x16x32_bf16 v[28:31], v[170:173], v[192:195], v[28:31]
	v_mfma_f32_16x16x32_bf16 v[24:27], v[178:181], v[192:195], v[24:27]
	v_mfma_f32_16x16x32_bf16 v[20:23], v[170:173], v[200:203], v[20:23]
	v_mfma_f32_16x16x32_bf16 v[16:19], v[178:181], v[200:203], v[16:19]
	v_mfma_f32_16x16x32_bf16 v[12:15], v[170:173], v[228:231], v[12:15]
	v_mfma_f32_16x16x32_bf16 v[8:11], v[178:181], v[228:231], v[8:11]
	v_mfma_f32_16x16x32_bf16 v[4:7], v[170:173], v[236:239], v[4:7]
	v_mfma_f32_16x16x32_bf16 v[0:3], v[178:181], v[236:239], v[0:3]
	v_mfma_f32_16x16x32_bf16 v[28:31], v[174:177], v[196:199], v[28:31]
	v_mfma_f32_16x16x32_bf16 v[24:27], v[188:191], v[196:199], v[24:27]
	v_mfma_f32_16x16x32_bf16 v[20:23], v[174:177], v[224:227], v[20:23]
	v_mfma_f32_16x16x32_bf16 v[16:19], v[188:191], v[224:227], v[16:19]
	v_mfma_f32_16x16x32_bf16 v[12:15], v[174:177], v[232:235], v[12:15]
	v_mfma_f32_16x16x32_bf16 v[8:11], v[188:191], v[232:235], v[8:11]
	v_mfma_f32_16x16x32_bf16 v[4:7], v[174:177], v[240:243], v[4:7]
	v_mfma_f32_16x16x32_bf16 v[0:3], v[188:191], v[240:243], v[0:3]
	s_setprio 0
	s_barrier
	s_add_i32 s9, 0, 0x18000
	v_add_u32_e32 v153, s9, v148
	s_add_i32 s26, 0, 0x1c000
	ds_read_b128 v[154:157], v153
	ds_read_b128 v[158:161], v153 offset:1024
	ds_read_b128 v[162:165], v153 offset:2048
	ds_read_b128 v[166:169], v153 offset:3072
	v_add_u32_e32 v153, s26, v148
	ds_read_b128 v[170:173], v153
	ds_read_b128 v[174:177], v153 offset:1024
	ds_read_b128 v[178:181], v153 offset:2048
	ds_read_b128 v[188:191], v153 offset:3072
	s_add_u32 s2, s2, s58
	s_addc_u32 s3, s3, 0
	s_mov_b32 m0, s10
	v_lshl_add_u64 v[212:213], s[2:3], 0, v[130:131]
	ds_read_b128 v[192:195], v149 offset:32768
	ds_read_b128 v[196:199], v149 offset:33792
	ds_read_b128 v[200:203], v149 offset:34816
	ds_read_b128 v[224:227], v149 offset:35840
	ds_read_b128 v[228:231], v149 offset:36864
	ds_read_b128 v[232:235], v149 offset:37888
	ds_read_b128 v[236:239], v149 offset:38912
	ds_read_b128 v[240:243], v149 offset:39936
	global_load_lds_dwordx4 v[212:213], off
	v_lshl_add_u64 v[212:213], s[2:3], 0, v[134:135]
	s_mov_b32 m0, s11
	s_nop 0
	global_load_lds_dwordx4 v[212:213], off
	s_waitcnt vmcnt(8)
	s_waitcnt lgkmcnt(0)
	s_barrier
	s_setprio 1
	s_waitcnt lgkmcnt(0)
	v_mfma_f32_16x16x32_bf16 v[124:127], v[154:157], v[192:195], v[124:127]
	v_mfma_f32_16x16x32_bf16 v[120:123], v[162:165], v[192:195], v[120:123]
	v_mfma_f32_16x16x32_bf16 v[116:119], v[154:157], v[200:203], v[116:119]
	v_mfma_f32_16x16x32_bf16 v[112:115], v[162:165], v[200:203], v[112:115]
	v_mfma_f32_16x16x32_bf16 v[108:111], v[154:157], v[228:231], v[108:111]
	v_mfma_f32_16x16x32_bf16 v[104:107], v[162:165], v[228:231], v[104:107]
	v_mfma_f32_16x16x32_bf16 v[100:103], v[154:157], v[236:239], v[100:103]
	v_mfma_f32_16x16x32_bf16 v[96:99], v[162:165], v[236:239], v[96:99]
	v_mfma_f32_16x16x32_bf16 v[124:127], v[158:161], v[196:199], v[124:127]
	v_mfma_f32_16x16x32_bf16 v[120:123], v[166:169], v[196:199], v[120:123]
	v_mfma_f32_16x16x32_bf16 v[116:119], v[158:161], v[224:227], v[116:119]
	v_mfma_f32_16x16x32_bf16 v[112:115], v[166:169], v[224:227], v[112:115]
	v_mfma_f32_16x16x32_bf16 v[108:111], v[158:161], v[232:235], v[108:111]
	v_mfma_f32_16x16x32_bf16 v[104:107], v[166:169], v[232:235], v[104:107]
	v_mfma_f32_16x16x32_bf16 v[100:103], v[158:161], v[240:243], v[100:103]
	v_mfma_f32_16x16x32_bf16 v[96:99], v[166:169], v[240:243], v[96:99]
	v_mfma_f32_16x16x32_bf16 v[92:95], v[170:173], v[192:195], v[92:95]
	v_mfma_f32_16x16x32_bf16 v[88:91], v[178:181], v[192:195], v[88:91]
	v_mfma_f32_16x16x32_bf16 v[84:87], v[170:173], v[200:203], v[84:87]
	v_mfma_f32_16x16x32_bf16 v[80:83], v[178:181], v[200:203], v[80:83]
	v_mfma_f32_16x16x32_bf16 v[76:79], v[170:173], v[228:231], v[76:79]
	v_mfma_f32_16x16x32_bf16 v[72:75], v[178:181], v[228:231], v[72:75]
	v_mfma_f32_16x16x32_bf16 v[68:71], v[170:173], v[236:239], v[68:71]
	v_mfma_f32_16x16x32_bf16 v[64:67], v[178:181], v[236:239], v[64:67]
	v_mfma_f32_16x16x32_bf16 v[92:95], v[174:177], v[196:199], v[92:95]
	v_mfma_f32_16x16x32_bf16 v[88:91], v[188:191], v[196:199], v[88:91]
	v_mfma_f32_16x16x32_bf16 v[84:87], v[174:177], v[224:227], v[84:87]
	v_mfma_f32_16x16x32_bf16 v[80:83], v[188:191], v[224:227], v[80:83]
	v_mfma_f32_16x16x32_bf16 v[76:79], v[174:177], v[232:235], v[76:79]
	v_mfma_f32_16x16x32_bf16 v[72:75], v[188:191], v[232:235], v[72:75]
	v_mfma_f32_16x16x32_bf16 v[68:71], v[174:177], v[240:243], v[68:71]
	v_mfma_f32_16x16x32_bf16 v[64:67], v[188:191], v[240:243], v[64:67]
	s_setprio 0
	s_barrier
; #define PG8_STAGE(bufoff, gbase, voff) do { _Pragma("unroll") for (int _i = 0; _i < 2; ++_i) \
;         __builtin_amdgcn_global_load_lds((const unsigned*)((const char*)(gbase) + (voff)[_i]), (LAS unsigned*)(lds + (bufoff) + ldsw + _i * 8192), 16, 0, 0); } while (0)
; #define PG8_LDA(dst, b, h) do { _Pragma("unroll") for (int m = 0; m < 4; ++m) _Pragma("unroll") for (int k = 0; k < 2; ++k) dst[m][k] = *(const LAS bf16x8*)(lds + PG8_SA(b, h) + aoff + m * 2048 + k * 1024); } while (0)
; #define PG8_MMA(ai, bj, At, Bt) do { __builtin_amdgcn_s_setprio(1); _Pragma("unroll") for (int m = 0; m < 4; ++m) _Pragma("unroll") for (int n = 0; n < 2; ++n) _Pragma("unroll") for (int k = 0; k < 2; ++k) \
;         acc[ai][bj][m][n] = __builtin_amdgcn_mfma_f32_16x16x32_bf16(Bt[n][k], At[m][k], acc[ai][bj][m][n], 0, 0, 0); __builtin_amdgcn_s_setprio(0); } while (0)
; #define PG8_WAIT_V(n) asm volatile("s_waitcnt vmcnt(" #n ")" ::: "memory")
; #define PG8_WAIT_L(n) asm volatile("s_waitcnt lgkmcnt(" #n ")" ::: "memory")
; #define PG8_BAR __builtin_amdgcn_s_barrier()
; #define PG8_SCHED __builtin_amdgcn_sched_barrier(0)
;     ...
;             PG8_LDA(At, 1, 1); PG8_STAGE(PG8_SB(1, 0), b3, voffB); PG8_STAGE(PG8_SB(1, 1), b3 + hstepB, voffB); PG8_STAGE(PG8_SA(1, 0), a3, voffA);
;             PG8_WAIT_V(8); PG8_WAIT_L(0); PG8_BAR; PG8_MMA(1, 0, At, B0); PG8_MMA(1, 1, At, B1); PG8_BAR; PG8_SCHED;
;         }
;         if (wr == 0) PG8_BAR;
	s_add_i32 s2, s9, s40
	v_lshl_add_u64 v[212:213], v[244:245], 0, s[70:71]
	s_mov_b32 m0, s2
	ds_read_b128 v[192:195], v149 offset:49152
	ds_read_b128 v[196:199], v149 offset:50176
	ds_read_b128 v[200:203], v149 offset:51200
	ds_read_b128 v[224:227], v149 offset:52224
	ds_read_b128 v[228:231], v149 offset:53248
	ds_read_b128 v[232:235], v149 offset:54272
	ds_read_b128 v[236:239], v149 offset:55296
	ds_read_b128 v[240:243], v149 offset:56320
	global_load_lds_dwordx4 v[212:213], off
	v_lshl_add_u64 v[212:213], v[246:247], 0, s[70:71]
	s_add_i32 m0, s2, 0x2000
	s_add_i32 s2, s26, s40
	global_load_lds_dwordx4 v[212:213], off
	v_lshl_add_u64 v[212:213], v[248:249], 0, s[70:71]
	s_mov_b32 m0, s2
	v_lshl_add_u64 v[204:205], v[204:205], 0, s[70:71]
	global_load_lds_dwordx4 v[212:213], off
	s_add_i32 m0, s2, 0x2000
	s_nop 0
	global_load_lds_dwordx4 v[204:205], off
	v_lshl_add_u64 v[204:205], v[250:251], 0, s[70:71]
	s_mov_b32 m0, s51
	s_nop 0
	global_load_lds_dwordx4 v[204:205], off
	v_lshl_add_u64 v[204:205], v[218:219], 0, s[70:71]
	s_mov_b32 m0, s64
	s_nop 0
	global_load_lds_dwordx4 v[204:205], off
	s_waitcnt vmcnt(8)
	s_waitcnt lgkmcnt(0)
	s_barrier
	s_setprio 1
	s_waitcnt lgkmcnt(0)
	v_mfma_f32_16x16x32_bf16 v[60:63], v[154:157], v[192:195], v[60:63]
	v_mfma_f32_16x16x32_bf16 v[56:59], v[162:165], v[192:195], v[56:59]
	v_mfma_f32_16x16x32_bf16 v[52:55], v[154:157], v[200:203], v[52:55]
	v_mfma_f32_16x16x32_bf16 v[48:51], v[162:165], v[200:203], v[48:51]
	v_mfma_f32_16x16x32_bf16 v[44:47], v[154:157], v[228:231], v[44:47]
	v_mfma_f32_16x16x32_bf16 v[40:43], v[162:165], v[228:231], v[40:43]
	v_mfma_f32_16x16x32_bf16 v[36:39], v[154:157], v[236:239], v[36:39]
	v_mfma_f32_16x16x32_bf16 v[32:35], v[162:165], v[236:239], v[32:35]
	v_mfma_f32_16x16x32_bf16 v[60:63], v[158:161], v[196:199], v[60:63]
	v_mfma_f32_16x16x32_bf16 v[56:59], v[166:169], v[196:199], v[56:59]
	v_mfma_f32_16x16x32_bf16 v[52:55], v[158:161], v[224:227], v[52:55]
	v_mfma_f32_16x16x32_bf16 v[48:51], v[166:169], v[224:227], v[48:51]
	v_mfma_f32_16x16x32_bf16 v[44:47], v[158:161], v[232:235], v[44:47]
	v_mfma_f32_16x16x32_bf16 v[40:43], v[166:169], v[232:235], v[40:43]
	v_mfma_f32_16x16x32_bf16 v[36:39], v[158:161], v[240:243], v[36:39]
	v_mfma_f32_16x16x32_bf16 v[32:35], v[166:169], v[240:243], v[32:35]
	v_mfma_f32_16x16x32_bf16 v[28:31], v[170:173], v[192:195], v[28:31]
	v_mfma_f32_16x16x32_bf16 v[24:27], v[178:181], v[192:195], v[24:27]
	v_mfma_f32_16x16x32_bf16 v[20:23], v[170:173], v[200:203], v[20:23]
	v_mfma_f32_16x16x32_bf16 v[16:19], v[178:181], v[200:203], v[16:19]
	v_mfma_f32_16x16x32_bf16 v[12:15], v[170:173], v[228:231], v[12:15]
	v_mfma_f32_16x16x32_bf16 v[8:11], v[178:181], v[228:231], v[8:11]
	v_mfma_f32_16x16x32_bf16 v[4:7], v[170:173], v[236:239], v[4:7]
	v_mfma_f32_16x16x32_bf16 v[0:3], v[178:181], v[236:239], v[0:3]
	v_mfma_f32_16x16x32_bf16 v[28:31], v[174:177], v[196:199], v[28:31]
	v_mfma_f32_16x16x32_bf16 v[24:27], v[188:191], v[196:199], v[24:27]
	v_mfma_f32_16x16x32_bf16 v[20:23], v[174:177], v[224:227], v[20:23]
	v_mfma_f32_16x16x32_bf16 v[16:19], v[188:191], v[224:227], v[16:19]
	v_mfma_f32_16x16x32_bf16 v[12:15], v[174:177], v[232:235], v[12:15]
	v_mfma_f32_16x16x32_bf16 v[8:11], v[188:191], v[232:235], v[8:11]
	v_mfma_f32_16x16x32_bf16 v[4:7], v[174:177], v[240:243], v[4:7]
	v_mfma_f32_16x16x32_bf16 v[0:3], v[188:191], v[240:243], v[0:3]
	s_setprio 0
	s_barrier
	s_add_u32 s0, s0, 0x100
	s_addc_u32 s1, s1, 0
	v_lshl_add_u64 v[146:147], v[146:147], 0, s[94:95]
	v_lshl_add_u64 v[144:145], v[144:145], 0, s[94:95]
	s_cmp_ge_u32 s8, s48
	s_mov_b32 s2, s8
	s_cbranch_scc0 .LBB0_416
	v_readlane_b32 s0, v254, 45
	v_readlane_b32 s1, v254, 46
	s_and_b64 vcc, exec, s[0:1]
	s_cbranch_vccz .LBB0_419
	s_barrier
